# pp_v31 + IDX: end-of-unit vmcnt(0) (mask-store acks) removed; the seam's own drain covers those stores
# speedup vs baseline: 1.0053x; 1.0053x over previous
.LBB0_566:
	s_add_i32 s58, s58, 1
	s_cmp_lg_u32 s58, 4
	s_cbranch_scc0 .LBB0_816
